# Resid K-loop (FFN-down, W_o): last iteration of the last unit runs from a copy without the wasted restage of K-tiles 0/1 (14 LDS-DMA pieces per wave removed)
# speedup vs baseline: 1.0029x; 1.0015x over previous
; #define PG8_STAGE(bufoff, gbase, voff) do { _Pragma("unroll") for (int _i = 0; _i < 2; ++_i) \
;         __builtin_amdgcn_global_load_lds((const unsigned*)((const char*)(gbase) + (voff)[_i]), (PG8_LAS unsigned*)(lds + (bufoff) + ldsw + _i * 8192), 16, 0, 0); } while (0)
; #define PG8_LDA(dst, b, h) do { _Pragma("unroll") for (int m = 0; m < 4; ++m) _Pragma("unroll") for (int k = 0; k < 2; ++k) dst[m][k] = *(const PG8_LAS bf16x8*)(lds + PG8_SA(b, h) + aoff + m * 2048 + k * 1024); } while (0)
; #define PG8_LDB(dst, b, h) do { _Pragma("unroll") for (int n = 0; n < 2; ++n) _Pragma("unroll") for (int k = 0; k < 2; ++k) dst[n][k] = *(const PG8_LAS bf16x8*)(lds + PG8_SB(b, h) + boff + n * 2048 + k * 1024); } while (0)
; #define PG8_MMA(ai, bj, At, Bt) do { __builtin_amdgcn_s_setprio(1); _Pragma("unroll") for (int m = 0; m < 4; ++m) _Pragma("unroll") for (int n = 0; n < 2; ++n) _Pragma("unroll") for (int k = 0; k < 2; ++k) \
;         acc[ai][bj][m][n] = __builtin_amdgcn_mfma_f32_16x16x32_bf16(Bt[n][k], At[m][k], acc[ai][bj][m][n], 0, 0, 0); __builtin_amdgcn_s_setprio(0); } while (0)
; #define PG8_WAIT_V(n) asm volatile("s_waitcnt vmcnt(" #n ")" ::: "memory")
; #define PG8_WAIT_L(n) asm volatile("s_waitcnt lgkmcnt(" #n ")" ::: "memory")
; #define PG8_BAR __builtin_amdgcn_s_barrier()
; #define PG8_SCHED __builtin_amdgcn_sched_barrier(0)
; template <class Epi, class Sched, bool ALIGN_EPI = false, bool SP2 = false>
; __device__ __forceinline__ void gemm_phase(PG8_LAS unsigned char* lds, const Gemm g, const Sched& S, const Epi& E) {
;     ...
;             const bool last = (t == nt - 2);
;             const char* a1 = cA + (size_t)(t + 1) * kstep;
;             const char* a2 = last ? nA : cA + (size_t)(t + 2) * kstep; const char* b2 = last ? nB : cB + (size_t)(t + 2) * kstep;
;             const char* a3 = a2 + kstep; const char* b3 = b2 + kstep;
;             if (last && has_next) S.a_ready(nxt);
;             if constexpr (SP2) {
;             PG8_LDB(B0, 0, 0); PG8_LDB(B1, 0, 1); PG8_SCHED; PG8_LDA(At, 0, 0); PG8_STAGE(PG8_SA(1, 1), a1 + hstep, voffA);
;             PG8_WAIT_V(8); PG8_WAIT_L(0); PG8_BAR; PG8_MMA(0, 0, At, B0); PG8_MMA(0, 1, At, B1); PG8_BAR; PG8_SCHED;
;             PG8_LDA(At, 0, 1); PG8_STAGE(PG8_SB(0, 0), b2, voffB); PG8_STAGE(PG8_SB(0, 1), b2 + hstep, voffB); PG8_STAGE(PG8_SA(0, 0), a2, voffA);
.LBB0_589:
	s_add_i32 s62, s40, 2
	s_add_u32 s63, s22, 0x80
	s_addc_u32 s41, s23, 0
	s_add_i32 s66, 0, 0x10000
	s_cmp_eq_u32 s56, s40
	s_cselect_b32 s41, s1, s41
	s_cselect_b32 s40, s0, s63
	s_cselect_b32 s65, s21, s61
	s_cselect_b32 s64, s20, s60
	s_add_i32 s63, 0, 0x14000
	v_add_u32_e32 v144, s66, v218
	v_add_u32_e32 v160, s63, v218
	ds_read_b128 v[132:135], v144
	ds_read_b128 v[136:139], v144 offset:1024
	ds_read_b128 v[140:143], v144 offset:2048
	ds_read_b128 v[144:147], v144 offset:3072
	ds_read_b128 v[148:151], v160
	ds_read_b128 v[152:155], v160 offset:1024
	ds_read_b128 v[156:159], v160 offset:2048
	ds_read_b128 v[160:163], v160 offset:3072
	v_lshl_add_u64 v[214:215], s[22:23], 0, v[202:203]
	s_add_i32 m0, s48, 0xc000
	ds_read_b128 v[164:167], v220
	ds_read_b128 v[168:171], v220 offset:1024
	ds_read_b128 v[172:175], v220 offset:2048
	ds_read_b128 v[176:179], v220 offset:3072
	ds_read_b128 v[180:183], v220 offset:4096
	ds_read_b128 v[184:187], v220 offset:5120
	ds_read_b128 v[206:209], v220 offset:6144
	ds_read_b128 v[210:213], v220 offset:7168
	global_load_lds_dwordx4 v[214:215], off
	v_lshl_add_u64 v[214:215], s[22:23], 0, v[204:205]
	s_add_i32 m0, s48, 0xe000
	s_nop 0
	global_load_lds_dwordx4 v[214:215], off
	s_waitcnt vmcnt(8)
	s_waitcnt lgkmcnt(0)
	v_mfma_f32_16x16x32_bf16 v[128:131], v[132:135], v[164:167], v[128:131]
	v_mfma_f32_16x16x32_bf16 v[124:127], v[140:143], v[164:167], v[124:127]
	v_mfma_f32_16x16x32_bf16 v[112:115], v[132:135], v[172:175], v[112:115]
	v_mfma_f32_16x16x32_bf16 v[108:111], v[140:143], v[172:175], v[108:111]
	s_barrier
	s_setprio 1
	v_mfma_f32_16x16x32_bf16 v[96:99], v[132:135], v[180:183], v[96:99]
	v_mfma_f32_16x16x32_bf16 v[92:95], v[140:143], v[180:183], v[92:95]
	v_mfma_f32_16x16x32_bf16 v[80:83], v[132:135], v[206:209], v[80:83]
	v_mfma_f32_16x16x32_bf16 v[76:79], v[140:143], v[206:209], v[76:79]
	v_mfma_f32_16x16x32_bf16 v[128:131], v[136:139], v[168:171], v[128:131]
	v_mfma_f32_16x16x32_bf16 v[124:127], v[144:147], v[168:171], v[124:127]
	v_mfma_f32_16x16x32_bf16 v[112:115], v[136:139], v[176:179], v[112:115]
	v_mfma_f32_16x16x32_bf16 v[108:111], v[144:147], v[176:179], v[108:111]
	v_mfma_f32_16x16x32_bf16 v[96:99], v[136:139], v[184:187], v[96:99]
	v_mfma_f32_16x16x32_bf16 v[92:95], v[144:147], v[184:187], v[92:95]
	v_mfma_f32_16x16x32_bf16 v[80:83], v[136:139], v[210:213], v[80:83]
	v_mfma_f32_16x16x32_bf16 v[76:79], v[144:147], v[210:213], v[76:79]
	s_setprio 0
	s_setprio 1
	v_mfma_f32_16x16x32_bf16 v[120:123], v[148:151], v[164:167], v[120:123]
	v_mfma_f32_16x16x32_bf16 v[116:119], v[156:159], v[164:167], v[116:119]
	v_mfma_f32_16x16x32_bf16 v[104:107], v[148:151], v[172:175], v[104:107]
	v_mfma_f32_16x16x32_bf16 v[100:103], v[156:159], v[172:175], v[100:103]
	v_mfma_f32_16x16x32_bf16 v[88:91], v[148:151], v[180:183], v[88:91]
	v_mfma_f32_16x16x32_bf16 v[84:87], v[156:159], v[180:183], v[84:87]
	v_mfma_f32_16x16x32_bf16 v[72:75], v[148:151], v[206:209], v[72:75]
	v_mfma_f32_16x16x32_bf16 v[68:71], v[156:159], v[206:209], v[68:71]
	v_mfma_f32_16x16x32_bf16 v[120:123], v[152:155], v[168:171], v[120:123]
	v_mfma_f32_16x16x32_bf16 v[116:119], v[160:163], v[168:171], v[116:119]
	v_mfma_f32_16x16x32_bf16 v[104:107], v[152:155], v[176:179], v[104:107]
	v_mfma_f32_16x16x32_bf16 v[100:103], v[160:163], v[176:179], v[100:103]
	v_mfma_f32_16x16x32_bf16 v[88:91], v[152:155], v[184:187], v[88:91]
	v_mfma_f32_16x16x32_bf16 v[84:87], v[160:163], v[184:187], v[84:87]
	v_mfma_f32_16x16x32_bf16 v[72:75], v[152:155], v[210:213], v[72:75]
	v_mfma_f32_16x16x32_bf16 v[68:71], v[160:163], v[210:213], v[68:71]
	s_setprio 0
	s_barrier
	s_add_i32 s66, s66, s47
	v_lshl_add_u64 v[214:215], s[64:65], 0, v[196:197]
	s_mov_b32 m0, s66
	ds_read_b128 v[164:167], v220 offset:16384
	ds_read_b128 v[168:171], v220 offset:17408
	ds_read_b128 v[172:175], v220 offset:18432
	ds_read_b128 v[176:179], v220 offset:19456
	ds_read_b128 v[180:183], v220 offset:20480
	ds_read_b128 v[184:187], v220 offset:21504
	ds_read_b128 v[206:209], v220 offset:22528
	ds_read_b128 v[210:213], v220 offset:23552
	global_load_lds_dwordx4 v[214:215], off
	s_add_i32 m0, s66, 0x2000
	v_lshl_add_u64 v[216:217], s[64:65], 0, v[32:33]
	s_add_u32 s64, s64, s4
	s_addc_u32 s65, s65, 0
	s_add_i32 s63, s63, s47
	global_load_lds_dwordx4 v[216:217], off
	v_lshl_add_u64 v[222:223], s[64:65], 0, v[196:197]
	s_mov_b32 m0, s63
	v_lshl_add_u64 v[224:225], s[64:65], 0, v[32:33]
	global_load_lds_dwordx4 v[222:223], off
	s_add_i32 m0, s63, 0x2000
	v_lshl_add_u64 v[226:227], s[40:41], 0, v[190:191]
	global_load_lds_dwordx4 v[224:225], off
	s_mov_b32 m0, s48
	v_lshl_add_u64 v[236:237], s[40:41], 0, v[188:189]
	global_load_lds_dwordx4 v[226:227], off
	s_mov_b32 m0, s49
	s_nop 0
	global_load_lds_dwordx4 v[236:237], off
	s_waitcnt vmcnt(8)
	s_waitcnt lgkmcnt(0)
	v_mfma_f32_16x16x32_bf16 v[64:67], v[132:135], v[164:167], v[64:67]
	v_mfma_f32_16x16x32_bf16 v[60:63], v[140:143], v[164:167], v[60:63]
	v_mfma_f32_16x16x32_bf16 v[48:51], v[132:135], v[172:175], v[48:51]
	v_mfma_f32_16x16x32_bf16 v[44:47], v[140:143], v[172:175], v[44:47]
	s_barrier
; #define PG8_STAGE(bufoff, gbase, voff) do { _Pragma("unroll") for (int _i = 0; _i < 2; ++_i) \
;         __builtin_amdgcn_global_load_lds((const unsigned*)((const char*)(gbase) + (voff)[_i]), (PG8_LAS unsigned*)(lds + (bufoff) + ldsw + _i * 8192), 16, 0, 0); } while (0)
; #define PG8_LDA(dst, b, h) do { _Pragma("unroll") for (int m = 0; m < 4; ++m) _Pragma("unroll") for (int k = 0; k < 2; ++k) dst[m][k] = *(const PG8_LAS bf16x8*)(lds + PG8_SA(b, h) + aoff + m * 2048 + k * 1024); } while (0)
; #define PG8_LDB(dst, b, h) do { _Pragma("unroll") for (int n = 0; n < 2; ++n) _Pragma("unroll") for (int k = 0; k < 2; ++k) dst[n][k] = *(const PG8_LAS bf16x8*)(lds + PG8_SB(b, h) + boff + n * 2048 + k * 1024); } while (0)
; #define PG8_MMA(ai, bj, At, Bt) do { __builtin_amdgcn_s_setprio(1); _Pragma("unroll") for (int m = 0; m < 4; ++m) _Pragma("unroll") for (int n = 0; n < 2; ++n) _Pragma("unroll") for (int k = 0; k < 2; ++k) \
;         acc[ai][bj][m][n] = __builtin_amdgcn_mfma_f32_16x16x32_bf16(Bt[n][k], At[m][k], acc[ai][bj][m][n], 0, 0, 0); __builtin_amdgcn_s_setprio(0); } while (0)
; #define PG8_WAIT_V(n) asm volatile("s_waitcnt vmcnt(" #n ")" ::: "memory")
; #define PG8_WAIT_L(n) asm volatile("s_waitcnt lgkmcnt(" #n ")" ::: "memory")
; #define PG8_BAR __builtin_amdgcn_s_barrier()
; #define PG8_SCHED __builtin_amdgcn_sched_barrier(0)
; template <class Epi, class Sched, bool ALIGN_EPI = false, bool SP2 = false>
; __device__ __forceinline__ void gemm_phase(PG8_LAS unsigned char* lds, const Gemm g, const Sched& S, const Epi& E) {
;     ...
;             PG8_WAIT_V(8); PG8_WAIT_L(0); PG8_BAR; PG8_MMA(1, 0, At, B0); PG8_MMA(1, 1, At, B1); PG8_BAR; PG8_SCHED;
;             PG8_LDB(B0, 1, 0); PG8_LDB(B1, 1, 1); PG8_SCHED; PG8_LDA(At, 1, 0); PG8_STAGE(PG8_SA(0, 1), a2 + hstep, voffA);
;             PG8_WAIT_V(8); PG8_WAIT_L(0); PG8_BAR; PG8_MMA(0, 0, At, B0); PG8_MMA(0, 1, At, B1); PG8_BAR; PG8_SCHED;
	s_setprio 1
	v_mfma_f32_16x16x32_bf16 v[28:31], v[132:135], v[180:183], v[28:31]
	v_mfma_f32_16x16x32_bf16 v[24:27], v[140:143], v[180:183], v[24:27]
	v_mfma_f32_16x16x32_bf16 v[12:15], v[132:135], v[206:209], v[12:15]
	v_mfma_f32_16x16x32_bf16 v[8:11], v[140:143], v[206:209], v[8:11]
	v_mfma_f32_16x16x32_bf16 v[64:67], v[136:139], v[168:171], v[64:67]
	v_mfma_f32_16x16x32_bf16 v[60:63], v[144:147], v[168:171], v[60:63]
	v_mfma_f32_16x16x32_bf16 v[48:51], v[136:139], v[176:179], v[48:51]
	v_mfma_f32_16x16x32_bf16 v[44:47], v[144:147], v[176:179], v[44:47]
	v_mfma_f32_16x16x32_bf16 v[28:31], v[136:139], v[184:187], v[28:31]
	v_mfma_f32_16x16x32_bf16 v[24:27], v[144:147], v[184:187], v[24:27]
	v_mfma_f32_16x16x32_bf16 v[12:15], v[136:139], v[210:213], v[12:15]
	v_mfma_f32_16x16x32_bf16 v[8:11], v[144:147], v[210:213], v[8:11]
	s_setprio 0
	s_setprio 1
	v_mfma_f32_16x16x32_bf16 v[56:59], v[148:151], v[164:167], v[56:59]
	v_mfma_f32_16x16x32_bf16 v[52:55], v[156:159], v[164:167], v[52:55]
	v_mfma_f32_16x16x32_bf16 v[40:43], v[148:151], v[172:175], v[40:43]
	v_mfma_f32_16x16x32_bf16 v[36:39], v[156:159], v[172:175], v[36:39]
	v_mfma_f32_16x16x32_bf16 v[20:23], v[148:151], v[180:183], v[20:23]
	v_mfma_f32_16x16x32_bf16 v[16:19], v[156:159], v[180:183], v[16:19]
	v_mfma_f32_16x16x32_bf16 v[4:7], v[148:151], v[206:209], v[4:7]
	v_mfma_f32_16x16x32_bf16 v[0:3], v[156:159], v[206:209], v[0:3]
	v_mfma_f32_16x16x32_bf16 v[56:59], v[152:155], v[168:171], v[56:59]
	v_mfma_f32_16x16x32_bf16 v[52:55], v[160:163], v[168:171], v[52:55]
	v_mfma_f32_16x16x32_bf16 v[40:43], v[152:155], v[176:179], v[40:43]
	v_mfma_f32_16x16x32_bf16 v[36:39], v[160:163], v[176:179], v[36:39]
	v_mfma_f32_16x16x32_bf16 v[20:23], v[152:155], v[184:187], v[20:23]
	v_mfma_f32_16x16x32_bf16 v[16:19], v[160:163], v[184:187], v[16:19]
	v_mfma_f32_16x16x32_bf16 v[4:7], v[152:155], v[210:213], v[4:7]
	v_mfma_f32_16x16x32_bf16 v[0:3], v[160:163], v[210:213], v[0:3]
	s_setprio 0
	s_barrier
	s_add_i32 s63, 0, 0x18000
	s_add_i32 s64, 0, 0x1c000
	v_add_u32_e32 v144, s63, v218
	v_add_u32_e32 v160, s64, v218
	ds_read_b128 v[132:135], v144
	ds_read_b128 v[136:139], v144 offset:1024
	ds_read_b128 v[140:143], v144 offset:2048
	ds_read_b128 v[144:147], v144 offset:3072
	ds_read_b128 v[148:151], v160
	ds_read_b128 v[152:155], v160 offset:1024
	ds_read_b128 v[156:159], v160 offset:2048
	ds_read_b128 v[160:163], v160 offset:3072
	s_add_u32 s40, s40, s4
	s_addc_u32 s41, s41, 0
	s_mov_b32 m0, s50
	v_lshl_add_u64 v[238:239], s[40:41], 0, v[190:191]
	ds_read_b128 v[164:167], v220 offset:32768
	ds_read_b128 v[168:171], v220 offset:33792
	ds_read_b128 v[172:175], v220 offset:34816
	ds_read_b128 v[176:179], v220 offset:35840
	ds_read_b128 v[180:183], v220 offset:36864
	ds_read_b128 v[184:187], v220 offset:37888
	ds_read_b128 v[206:209], v220 offset:38912
	ds_read_b128 v[210:213], v220 offset:39936
	global_load_lds_dwordx4 v[238:239], off
	v_lshl_add_u64 v[238:239], s[40:41], 0, v[188:189]
	s_mov_b32 m0, s51
	s_nop 0
	global_load_lds_dwordx4 v[238:239], off
	s_waitcnt vmcnt(8)
	s_waitcnt lgkmcnt(0)
	v_mfma_f32_16x16x32_bf16 v[128:131], v[132:135], v[164:167], v[128:131]
	v_mfma_f32_16x16x32_bf16 v[124:127], v[140:143], v[164:167], v[124:127]
	v_mfma_f32_16x16x32_bf16 v[112:115], v[132:135], v[172:175], v[112:115]
	v_mfma_f32_16x16x32_bf16 v[108:111], v[140:143], v[172:175], v[108:111]
	s_barrier
	s_setprio 1
	v_mfma_f32_16x16x32_bf16 v[96:99], v[132:135], v[180:183], v[96:99]
	v_mfma_f32_16x16x32_bf16 v[92:95], v[140:143], v[180:183], v[92:95]
	v_mfma_f32_16x16x32_bf16 v[80:83], v[132:135], v[206:209], v[80:83]
	v_mfma_f32_16x16x32_bf16 v[76:79], v[140:143], v[206:209], v[76:79]
	v_mfma_f32_16x16x32_bf16 v[128:131], v[136:139], v[168:171], v[128:131]
	v_mfma_f32_16x16x32_bf16 v[124:127], v[144:147], v[168:171], v[124:127]
	v_mfma_f32_16x16x32_bf16 v[112:115], v[136:139], v[176:179], v[112:115]
	v_mfma_f32_16x16x32_bf16 v[108:111], v[144:147], v[176:179], v[108:111]
	v_mfma_f32_16x16x32_bf16 v[96:99], v[136:139], v[184:187], v[96:99]
	v_mfma_f32_16x16x32_bf16 v[92:95], v[144:147], v[184:187], v[92:95]
	v_mfma_f32_16x16x32_bf16 v[80:83], v[136:139], v[210:213], v[80:83]
	v_mfma_f32_16x16x32_bf16 v[76:79], v[144:147], v[210:213], v[76:79]
	s_setprio 0
	s_setprio 1
	v_mfma_f32_16x16x32_bf16 v[120:123], v[148:151], v[164:167], v[120:123]
	v_mfma_f32_16x16x32_bf16 v[116:119], v[156:159], v[164:167], v[116:119]
	v_mfma_f32_16x16x32_bf16 v[104:107], v[148:151], v[172:175], v[104:107]
	v_mfma_f32_16x16x32_bf16 v[100:103], v[156:159], v[172:175], v[100:103]
	v_mfma_f32_16x16x32_bf16 v[88:91], v[148:151], v[180:183], v[88:91]
	v_mfma_f32_16x16x32_bf16 v[84:87], v[156:159], v[180:183], v[84:87]
	v_mfma_f32_16x16x32_bf16 v[72:75], v[148:151], v[206:209], v[72:75]
	v_mfma_f32_16x16x32_bf16 v[68:71], v[156:159], v[206:209], v[68:71]
	v_mfma_f32_16x16x32_bf16 v[120:123], v[152:155], v[168:171], v[120:123]
	v_mfma_f32_16x16x32_bf16 v[116:119], v[160:163], v[168:171], v[116:119]
	v_mfma_f32_16x16x32_bf16 v[104:107], v[152:155], v[176:179], v[104:107]
	v_mfma_f32_16x16x32_bf16 v[100:103], v[160:163], v[176:179], v[100:103]
	v_mfma_f32_16x16x32_bf16 v[88:91], v[152:155], v[184:187], v[88:91]
	v_mfma_f32_16x16x32_bf16 v[84:87], v[160:163], v[184:187], v[84:87]
	v_mfma_f32_16x16x32_bf16 v[72:75], v[152:155], v[210:213], v[72:75]
	v_mfma_f32_16x16x32_bf16 v[68:71], v[160:163], v[210:213], v[68:71]
	s_setprio 0
	s_barrier
; #define PG8_STAGE(bufoff, gbase, voff) do { _Pragma("unroll") for (int _i = 0; _i < 2; ++_i) \
;         __builtin_amdgcn_global_load_lds((const unsigned*)((const char*)(gbase) + (voff)[_i]), (PG8_LAS unsigned*)(lds + (bufoff) + ldsw + _i * 8192), 16, 0, 0); } while (0)
; #define PG8_LDA(dst, b, h) do { _Pragma("unroll") for (int m = 0; m < 4; ++m) _Pragma("unroll") for (int k = 0; k < 2; ++k) dst[m][k] = *(const PG8_LAS bf16x8*)(lds + PG8_SA(b, h) + aoff + m * 2048 + k * 1024); } while (0)
; #define PG8_LDB(dst, b, h) do { _Pragma("unroll") for (int n = 0; n < 2; ++n) _Pragma("unroll") for (int k = 0; k < 2; ++k) dst[n][k] = *(const PG8_LAS bf16x8*)(lds + PG8_SB(b, h) + boff + n * 2048 + k * 1024); } while (0)
; #define PG8_MMA(ai, bj, At, Bt) do { __builtin_amdgcn_s_setprio(1); _Pragma("unroll") for (int m = 0; m < 4; ++m) _Pragma("unroll") for (int n = 0; n < 2; ++n) _Pragma("unroll") for (int k = 0; k < 2; ++k) \
;         acc[ai][bj][m][n] = __builtin_amdgcn_mfma_f32_16x16x32_bf16(Bt[n][k], At[m][k], acc[ai][bj][m][n], 0, 0, 0); __builtin_amdgcn_s_setprio(0); } while (0)
; #define PG8_WAIT_V(n) asm volatile("s_waitcnt vmcnt(" #n ")" ::: "memory")
; template <class Epi, class Sched, bool ALIGN_EPI = false, bool SP2 = false>
; __device__ __forceinline__ void gemm_phase(PG8_LAS unsigned char* lds, const Gemm g, const Sched& S, const Epi& E) {
;     ...
;             PG8_LDB(B0, 0, 0); PG8_LDB(B1, 0, 1); PG8_SCHED; PG8_LDA(At, 0, 0); PG8_STAGE(PG8_SA(1, 1), a1 + hstep, voffA);
;             PG8_WAIT_V(8); PG8_WAIT_L(0); PG8_BAR; PG8_MMA(0, 0, At, B0); PG8_MMA(0, 1, At, B1); PG8_BAR; PG8_SCHED;
;             PG8_LDA(At, 0, 1); PG8_STAGE(PG8_SB(0, 0), b2, voffB); PG8_STAGE(PG8_SB(0, 1), b2 + hstep, voffB); PG8_STAGE(PG8_SA(0, 0), a2, voffA);
;             PG8_WAIT_V(8); PG8_WAIT_L(0); PG8_BAR; PG8_MMA(1, 0, At, B0); PG8_MMA(1, 1, At, B1); PG8_BAR; PG8_SCHED;
;             PG8_LDB(B0, 1, 0); PG8_LDB(B1, 1, 1); PG8_SCHED; PG8_LDA(At, 1, 0); PG8_STAGE(PG8_SA(0, 1), a2 + hstep, voffA);
;             PG8_WAIT_V(8); PG8_WAIT_L(0); PG8_BAR; PG8_MMA(0, 0, At, B0); PG8_MMA(0, 1, At, B1); PG8_BAR; PG8_SCHED;
;             PG8_LDA(At, 1, 1); PG8_STAGE(PG8_SB(1, 0), b3, voffB); PG8_STAGE(PG8_SB(1, 1), b3 + hstep, voffB); PG8_STAGE(PG8_SA(1, 0), a3, voffA);
;             PG8_WAIT_V(8); PG8_WAIT_L(0); PG8_BAR; PG8_MMA(1, 0, At, B0); PG8_MMA(1, 1, At, B1); PG8_BAR; PG8_SCHED;
	s_add_i32 s40, s63, s47
	v_lshl_add_u64 v[214:215], v[214:215], 0, s[36:37]
	s_mov_b32 m0, s40
	ds_read_b128 v[164:167], v220 offset:49152
	ds_read_b128 v[168:171], v220 offset:50176
	ds_read_b128 v[172:175], v220 offset:51200
	ds_read_b128 v[176:179], v220 offset:52224
	ds_read_b128 v[180:183], v220 offset:53248
	ds_read_b128 v[184:187], v220 offset:54272
	ds_read_b128 v[206:209], v220 offset:55296
	ds_read_b128 v[210:213], v220 offset:56320
	global_load_lds_dwordx4 v[214:215], off
	v_lshl_add_u64 v[214:215], v[216:217], 0, s[36:37]
	s_add_i32 m0, s40, 0x2000
	s_add_i32 s40, s64, s47
	global_load_lds_dwordx4 v[214:215], off
	v_lshl_add_u64 v[214:215], v[222:223], 0, s[36:37]
	s_mov_b32 m0, s40
	s_nop 0
	global_load_lds_dwordx4 v[214:215], off
	v_lshl_add_u64 v[214:215], v[224:225], 0, s[36:37]
	s_add_i32 m0, s40, 0x2000
	s_nop 0
	global_load_lds_dwordx4 v[214:215], off
	v_lshl_add_u64 v[214:215], v[226:227], 0, s[36:37]
	s_mov_b32 m0, s52
	s_nop 0
	global_load_lds_dwordx4 v[214:215], off
	v_lshl_add_u64 v[214:215], v[236:237], 0, s[36:37]
	s_mov_b32 m0, s53
	s_nop 0
	global_load_lds_dwordx4 v[214:215], off
	s_waitcnt vmcnt(8)
	s_waitcnt lgkmcnt(0)
	v_mfma_f32_16x16x32_bf16 v[64:67], v[132:135], v[164:167], v[64:67]
	v_mfma_f32_16x16x32_bf16 v[60:63], v[140:143], v[164:167], v[60:63]
	v_mfma_f32_16x16x32_bf16 v[48:51], v[132:135], v[172:175], v[48:51]
	v_mfma_f32_16x16x32_bf16 v[44:47], v[140:143], v[172:175], v[44:47]
	s_barrier
	s_setprio 1
	v_mfma_f32_16x16x32_bf16 v[28:31], v[132:135], v[180:183], v[28:31]
	v_mfma_f32_16x16x32_bf16 v[24:27], v[140:143], v[180:183], v[24:27]
	v_mfma_f32_16x16x32_bf16 v[12:15], v[132:135], v[206:209], v[12:15]
	v_mfma_f32_16x16x32_bf16 v[8:11], v[140:143], v[206:209], v[8:11]
	v_mfma_f32_16x16x32_bf16 v[64:67], v[136:139], v[168:171], v[64:67]
	v_mfma_f32_16x16x32_bf16 v[60:63], v[144:147], v[168:171], v[60:63]
	v_mfma_f32_16x16x32_bf16 v[48:51], v[136:139], v[176:179], v[48:51]
	v_mfma_f32_16x16x32_bf16 v[44:47], v[144:147], v[176:179], v[44:47]
	v_mfma_f32_16x16x32_bf16 v[28:31], v[136:139], v[184:187], v[28:31]
	v_mfma_f32_16x16x32_bf16 v[24:27], v[144:147], v[184:187], v[24:27]
	v_mfma_f32_16x16x32_bf16 v[12:15], v[136:139], v[210:213], v[12:15]
	v_mfma_f32_16x16x32_bf16 v[8:11], v[144:147], v[210:213], v[8:11]
	s_setprio 0
	s_setprio 1
	v_mfma_f32_16x16x32_bf16 v[56:59], v[148:151], v[164:167], v[56:59]
	v_mfma_f32_16x16x32_bf16 v[52:55], v[156:159], v[164:167], v[52:55]
	v_mfma_f32_16x16x32_bf16 v[40:43], v[148:151], v[172:175], v[40:43]
	v_mfma_f32_16x16x32_bf16 v[36:39], v[156:159], v[172:175], v[36:39]
	v_mfma_f32_16x16x32_bf16 v[20:23], v[148:151], v[180:183], v[20:23]
	v_mfma_f32_16x16x32_bf16 v[16:19], v[156:159], v[180:183], v[16:19]
	v_mfma_f32_16x16x32_bf16 v[4:7], v[148:151], v[206:209], v[4:7]
	v_mfma_f32_16x16x32_bf16 v[0:3], v[156:159], v[206:209], v[0:3]
	v_mfma_f32_16x16x32_bf16 v[56:59], v[152:155], v[168:171], v[56:59]
	v_mfma_f32_16x16x32_bf16 v[52:55], v[160:163], v[168:171], v[52:55]
	v_mfma_f32_16x16x32_bf16 v[40:43], v[152:155], v[176:179], v[40:43]
	v_mfma_f32_16x16x32_bf16 v[36:39], v[160:163], v[176:179], v[36:39]
	v_mfma_f32_16x16x32_bf16 v[20:23], v[152:155], v[184:187], v[20:23]
	v_mfma_f32_16x16x32_bf16 v[16:19], v[160:163], v[184:187], v[16:19]
	v_mfma_f32_16x16x32_bf16 v[4:7], v[152:155], v[210:213], v[4:7]
	v_mfma_f32_16x16x32_bf16 v[0:3], v[160:163], v[210:213], v[0:3]
	s_setprio 0
	s_barrier
	s_add_u32 s22, s22, 0x100
	s_addc_u32 s23, s23, 0
	s_add_u32 s60, s60, 0x100
	s_addc_u32 s61, s61, 0
	s_cmp_ge_u32 s62, s55
	s_mov_b32 s40, s62
	s_cbranch_scc1 .Lkexit_rs
	s_cmp_eq_u32 s62, s56
	s_cbranch_scc0 .LBB0_589
	s_cmp_lg_u64 s[38:39], 0
	s_cbranch_scc0 .LBB0_589
.Ltail_rs:
	s_add_i32 s62, s40, 2
	s_add_u32 s63, s22, 0x80
	s_addc_u32 s41, s23, 0
	s_add_i32 s66, 0, 0x10000
	s_cmp_eq_u32 s56, s40
	s_cselect_b32 s41, s1, s41
	s_cselect_b32 s40, s0, s63
	s_cselect_b32 s65, s21, s61
	s_cselect_b32 s64, s20, s60
	s_add_i32 s63, 0, 0x14000
	v_add_u32_e32 v144, s66, v218
	v_add_u32_e32 v160, s63, v218
	ds_read_b128 v[132:135], v144
	ds_read_b128 v[136:139], v144 offset:1024
	ds_read_b128 v[140:143], v144 offset:2048
	ds_read_b128 v[144:147], v144 offset:3072
	ds_read_b128 v[148:151], v160
	ds_read_b128 v[152:155], v160 offset:1024
	ds_read_b128 v[156:159], v160 offset:2048
	ds_read_b128 v[160:163], v160 offset:3072
	v_lshl_add_u64 v[214:215], s[22:23], 0, v[202:203]
	s_add_i32 m0, s48, 0xc000
	ds_read_b128 v[164:167], v220
	ds_read_b128 v[168:171], v220 offset:1024
	ds_read_b128 v[172:175], v220 offset:2048
	ds_read_b128 v[176:179], v220 offset:3072
	ds_read_b128 v[180:183], v220 offset:4096
	ds_read_b128 v[184:187], v220 offset:5120
	ds_read_b128 v[206:209], v220 offset:6144
	ds_read_b128 v[210:213], v220 offset:7168
	global_load_lds_dwordx4 v[214:215], off
	v_lshl_add_u64 v[214:215], s[22:23], 0, v[204:205]
	s_add_i32 m0, s48, 0xe000
	s_nop 0
	global_load_lds_dwordx4 v[214:215], off
	s_waitcnt vmcnt(8)
	s_waitcnt lgkmcnt(0)
	v_mfma_f32_16x16x32_bf16 v[128:131], v[132:135], v[164:167], v[128:131]
	v_mfma_f32_16x16x32_bf16 v[124:127], v[140:143], v[164:167], v[124:127]
	v_mfma_f32_16x16x32_bf16 v[112:115], v[132:135], v[172:175], v[112:115]
	v_mfma_f32_16x16x32_bf16 v[108:111], v[140:143], v[172:175], v[108:111]
	s_barrier
; #define PG8_STAGE(bufoff, gbase, voff) do { _Pragma("unroll") for (int _i = 0; _i < 2; ++_i) \
;         __builtin_amdgcn_global_load_lds((const unsigned*)((const char*)(gbase) + (voff)[_i]), (PG8_LAS unsigned*)(lds + (bufoff) + ldsw + _i * 8192), 16, 0, 0); } while (0)
; #define PG8_LDA(dst, b, h) do { _Pragma("unroll") for (int m = 0; m < 4; ++m) _Pragma("unroll") for (int k = 0; k < 2; ++k) dst[m][k] = *(const PG8_LAS bf16x8*)(lds + PG8_SA(b, h) + aoff + m * 2048 + k * 1024); } while (0)
; #define PG8_MMA(ai, bj, At, Bt) do { __builtin_amdgcn_s_setprio(1); _Pragma("unroll") for (int m = 0; m < 4; ++m) _Pragma("unroll") for (int n = 0; n < 2; ++n) _Pragma("unroll") for (int k = 0; k < 2; ++k) \
;         acc[ai][bj][m][n] = __builtin_amdgcn_mfma_f32_16x16x32_bf16(Bt[n][k], At[m][k], acc[ai][bj][m][n], 0, 0, 0); __builtin_amdgcn_s_setprio(0); } while (0)
; #define PG8_WAIT_V(n) asm volatile("s_waitcnt vmcnt(" #n ")" ::: "memory")
; #define PG8_WAIT_L(n) asm volatile("s_waitcnt lgkmcnt(" #n ")" ::: "memory")
; #define PG8_BAR __builtin_amdgcn_s_barrier()
; #define PG8_SCHED __builtin_amdgcn_sched_barrier(0)
; template <class Epi, class Sched, bool ALIGN_EPI = false, bool SP2 = false>
; __device__ __forceinline__ void gemm_phase(PG8_LAS unsigned char* lds, const Gemm g, const Sched& S, const Epi& E) {
;     ...
;             PG8_WAIT_V(8); PG8_WAIT_L(0); PG8_BAR; PG8_MMA(0, 0, At, B0); PG8_MMA(0, 1, At, B1); PG8_BAR; PG8_SCHED;
;             PG8_LDA(At, 0, 1); PG8_STAGE(PG8_SB(0, 0), b2, voffB); PG8_STAGE(PG8_SB(0, 1), b2 + hstep, voffB); PG8_STAGE(PG8_SA(0, 0), a2, voffA);
;             PG8_WAIT_V(8); PG8_WAIT_L(0); PG8_BAR; PG8_MMA(1, 0, At, B0); PG8_MMA(1, 1, At, B1); PG8_BAR; PG8_SCHED;
	s_setprio 1
	v_mfma_f32_16x16x32_bf16 v[96:99], v[132:135], v[180:183], v[96:99]
	v_mfma_f32_16x16x32_bf16 v[92:95], v[140:143], v[180:183], v[92:95]
	v_mfma_f32_16x16x32_bf16 v[80:83], v[132:135], v[206:209], v[80:83]
	v_mfma_f32_16x16x32_bf16 v[76:79], v[140:143], v[206:209], v[76:79]
	v_mfma_f32_16x16x32_bf16 v[128:131], v[136:139], v[168:171], v[128:131]
	v_mfma_f32_16x16x32_bf16 v[124:127], v[144:147], v[168:171], v[124:127]
	v_mfma_f32_16x16x32_bf16 v[112:115], v[136:139], v[176:179], v[112:115]
	v_mfma_f32_16x16x32_bf16 v[108:111], v[144:147], v[176:179], v[108:111]
	v_mfma_f32_16x16x32_bf16 v[96:99], v[136:139], v[184:187], v[96:99]
	v_mfma_f32_16x16x32_bf16 v[92:95], v[144:147], v[184:187], v[92:95]
	v_mfma_f32_16x16x32_bf16 v[80:83], v[136:139], v[210:213], v[80:83]
	v_mfma_f32_16x16x32_bf16 v[76:79], v[144:147], v[210:213], v[76:79]
	s_setprio 0
	s_setprio 1
	v_mfma_f32_16x16x32_bf16 v[120:123], v[148:151], v[164:167], v[120:123]
	v_mfma_f32_16x16x32_bf16 v[116:119], v[156:159], v[164:167], v[116:119]
	v_mfma_f32_16x16x32_bf16 v[104:107], v[148:151], v[172:175], v[104:107]
	v_mfma_f32_16x16x32_bf16 v[100:103], v[156:159], v[172:175], v[100:103]
	v_mfma_f32_16x16x32_bf16 v[88:91], v[148:151], v[180:183], v[88:91]
	v_mfma_f32_16x16x32_bf16 v[84:87], v[156:159], v[180:183], v[84:87]
	v_mfma_f32_16x16x32_bf16 v[72:75], v[148:151], v[206:209], v[72:75]
	v_mfma_f32_16x16x32_bf16 v[68:71], v[156:159], v[206:209], v[68:71]
	v_mfma_f32_16x16x32_bf16 v[120:123], v[152:155], v[168:171], v[120:123]
	v_mfma_f32_16x16x32_bf16 v[116:119], v[160:163], v[168:171], v[116:119]
	v_mfma_f32_16x16x32_bf16 v[104:107], v[152:155], v[176:179], v[104:107]
	v_mfma_f32_16x16x32_bf16 v[100:103], v[160:163], v[176:179], v[100:103]
	v_mfma_f32_16x16x32_bf16 v[88:91], v[152:155], v[184:187], v[88:91]
	v_mfma_f32_16x16x32_bf16 v[84:87], v[160:163], v[184:187], v[84:87]
	v_mfma_f32_16x16x32_bf16 v[72:75], v[152:155], v[210:213], v[72:75]
	v_mfma_f32_16x16x32_bf16 v[68:71], v[160:163], v[210:213], v[68:71]
	s_setprio 0
	s_barrier
	s_add_i32 s66, s66, s47
	v_lshl_add_u64 v[214:215], s[64:65], 0, v[196:197]
	s_mov_b32 m0, s66
	ds_read_b128 v[164:167], v220 offset:16384
	ds_read_b128 v[168:171], v220 offset:17408
	ds_read_b128 v[172:175], v220 offset:18432
	ds_read_b128 v[176:179], v220 offset:19456
	ds_read_b128 v[180:183], v220 offset:20480
	ds_read_b128 v[184:187], v220 offset:21504
	ds_read_b128 v[206:209], v220 offset:22528
	ds_read_b128 v[210:213], v220 offset:23552
	s_add_i32 m0, s66, 0x2000
	v_lshl_add_u64 v[216:217], s[64:65], 0, v[32:33]
	s_add_u32 s64, s64, s4
	s_addc_u32 s65, s65, 0
	s_add_i32 s63, s63, s47
	v_lshl_add_u64 v[222:223], s[64:65], 0, v[196:197]
	s_mov_b32 m0, s63
	v_lshl_add_u64 v[224:225], s[64:65], 0, v[32:33]
	s_add_i32 m0, s63, 0x2000
	v_lshl_add_u64 v[226:227], s[40:41], 0, v[190:191]
	s_mov_b32 m0, s48
	v_lshl_add_u64 v[236:237], s[40:41], 0, v[188:189]
	s_mov_b32 m0, s49
	s_nop 0
	s_waitcnt vmcnt(2)
	s_waitcnt lgkmcnt(0)
	v_mfma_f32_16x16x32_bf16 v[64:67], v[132:135], v[164:167], v[64:67]
	v_mfma_f32_16x16x32_bf16 v[60:63], v[140:143], v[164:167], v[60:63]
	v_mfma_f32_16x16x32_bf16 v[48:51], v[132:135], v[172:175], v[48:51]
	v_mfma_f32_16x16x32_bf16 v[44:47], v[140:143], v[172:175], v[44:47]
	s_barrier
	s_setprio 1
	v_mfma_f32_16x16x32_bf16 v[28:31], v[132:135], v[180:183], v[28:31]
	v_mfma_f32_16x16x32_bf16 v[24:27], v[140:143], v[180:183], v[24:27]
	v_mfma_f32_16x16x32_bf16 v[12:15], v[132:135], v[206:209], v[12:15]
	v_mfma_f32_16x16x32_bf16 v[8:11], v[140:143], v[206:209], v[8:11]
	v_mfma_f32_16x16x32_bf16 v[64:67], v[136:139], v[168:171], v[64:67]
	v_mfma_f32_16x16x32_bf16 v[60:63], v[144:147], v[168:171], v[60:63]
	v_mfma_f32_16x16x32_bf16 v[48:51], v[136:139], v[176:179], v[48:51]
	v_mfma_f32_16x16x32_bf16 v[44:47], v[144:147], v[176:179], v[44:47]
	v_mfma_f32_16x16x32_bf16 v[28:31], v[136:139], v[184:187], v[28:31]
	v_mfma_f32_16x16x32_bf16 v[24:27], v[144:147], v[184:187], v[24:27]
	v_mfma_f32_16x16x32_bf16 v[12:15], v[136:139], v[210:213], v[12:15]
	v_mfma_f32_16x16x32_bf16 v[8:11], v[144:147], v[210:213], v[8:11]
	s_setprio 0
	s_setprio 1
	v_mfma_f32_16x16x32_bf16 v[56:59], v[148:151], v[164:167], v[56:59]
	v_mfma_f32_16x16x32_bf16 v[52:55], v[156:159], v[164:167], v[52:55]
	v_mfma_f32_16x16x32_bf16 v[40:43], v[148:151], v[172:175], v[40:43]
	v_mfma_f32_16x16x32_bf16 v[36:39], v[156:159], v[172:175], v[36:39]
	v_mfma_f32_16x16x32_bf16 v[20:23], v[148:151], v[180:183], v[20:23]
	v_mfma_f32_16x16x32_bf16 v[16:19], v[156:159], v[180:183], v[16:19]
	v_mfma_f32_16x16x32_bf16 v[4:7], v[148:151], v[206:209], v[4:7]
	v_mfma_f32_16x16x32_bf16 v[0:3], v[156:159], v[206:209], v[0:3]
	v_mfma_f32_16x16x32_bf16 v[56:59], v[152:155], v[168:171], v[56:59]
	v_mfma_f32_16x16x32_bf16 v[52:55], v[160:163], v[168:171], v[52:55]
	v_mfma_f32_16x16x32_bf16 v[40:43], v[152:155], v[176:179], v[40:43]
	v_mfma_f32_16x16x32_bf16 v[36:39], v[160:163], v[176:179], v[36:39]
	v_mfma_f32_16x16x32_bf16 v[20:23], v[152:155], v[184:187], v[20:23]
	v_mfma_f32_16x16x32_bf16 v[16:19], v[160:163], v[184:187], v[16:19]
	v_mfma_f32_16x16x32_bf16 v[4:7], v[152:155], v[210:213], v[4:7]
	v_mfma_f32_16x16x32_bf16 v[0:3], v[160:163], v[210:213], v[0:3]
	s_setprio 0
	s_barrier
; #define PG8_STAGE(bufoff, gbase, voff) do { _Pragma("unroll") for (int _i = 0; _i < 2; ++_i) \
;         __builtin_amdgcn_global_load_lds((const unsigned*)((const char*)(gbase) + (voff)[_i]), (PG8_LAS unsigned*)(lds + (bufoff) + ldsw + _i * 8192), 16, 0, 0); } while (0)
; #define PG8_LDA(dst, b, h) do { _Pragma("unroll") for (int m = 0; m < 4; ++m) _Pragma("unroll") for (int k = 0; k < 2; ++k) dst[m][k] = *(const PG8_LAS bf16x8*)(lds + PG8_SA(b, h) + aoff + m * 2048 + k * 1024); } while (0)
; #define PG8_LDB(dst, b, h) do { _Pragma("unroll") for (int n = 0; n < 2; ++n) _Pragma("unroll") for (int k = 0; k < 2; ++k) dst[n][k] = *(const PG8_LAS bf16x8*)(lds + PG8_SB(b, h) + boff + n * 2048 + k * 1024); } while (0)
; #define PG8_MMA(ai, bj, At, Bt) do { __builtin_amdgcn_s_setprio(1); _Pragma("unroll") for (int m = 0; m < 4; ++m) _Pragma("unroll") for (int n = 0; n < 2; ++n) _Pragma("unroll") for (int k = 0; k < 2; ++k) \
;         acc[ai][bj][m][n] = __builtin_amdgcn_mfma_f32_16x16x32_bf16(Bt[n][k], At[m][k], acc[ai][bj][m][n], 0, 0, 0); __builtin_amdgcn_s_setprio(0); } while (0)
; #define PG8_WAIT_V(n) asm volatile("s_waitcnt vmcnt(" #n ")" ::: "memory")
; #define PG8_WAIT_L(n) asm volatile("s_waitcnt lgkmcnt(" #n ")" ::: "memory")
; #define PG8_BAR __builtin_amdgcn_s_barrier()
; #define PG8_SCHED __builtin_amdgcn_sched_barrier(0)
; template <class Epi, class Sched, bool ALIGN_EPI = false, bool SP2 = false>
; __device__ __forceinline__ void gemm_phase(PG8_LAS unsigned char* lds, const Gemm g, const Sched& S, const Epi& E) {
;     ...
;             PG8_LDB(B0, 1, 0); PG8_LDB(B1, 1, 1); PG8_SCHED; PG8_LDA(At, 1, 0); PG8_STAGE(PG8_SA(0, 1), a2 + hstep, voffA);
;             PG8_WAIT_V(8); PG8_WAIT_L(0); PG8_BAR; PG8_MMA(0, 0, At, B0); PG8_MMA(0, 1, At, B1); PG8_BAR; PG8_SCHED;
;             PG8_LDA(At, 1, 1); PG8_STAGE(PG8_SB(1, 0), b3, voffB); PG8_STAGE(PG8_SB(1, 1), b3 + hstep, voffB); PG8_STAGE(PG8_SA(1, 0), a3, voffA);
;             PG8_WAIT_V(8); PG8_WAIT_L(0); PG8_BAR; PG8_MMA(1, 0, At, B0); PG8_MMA(1, 1, At, B1); PG8_BAR; PG8_SCHED;
	s_add_i32 s63, 0, 0x18000
	s_add_i32 s64, 0, 0x1c000
	v_add_u32_e32 v144, s63, v218
	v_add_u32_e32 v160, s64, v218
	ds_read_b128 v[132:135], v144
	ds_read_b128 v[136:139], v144 offset:1024
	ds_read_b128 v[140:143], v144 offset:2048
	ds_read_b128 v[144:147], v144 offset:3072
	ds_read_b128 v[148:151], v160
	ds_read_b128 v[152:155], v160 offset:1024
	ds_read_b128 v[156:159], v160 offset:2048
	ds_read_b128 v[160:163], v160 offset:3072
	s_add_u32 s40, s40, s4
	s_addc_u32 s41, s41, 0
	s_mov_b32 m0, s50
	v_lshl_add_u64 v[238:239], s[40:41], 0, v[190:191]
	ds_read_b128 v[164:167], v220 offset:32768
	ds_read_b128 v[168:171], v220 offset:33792
	ds_read_b128 v[172:175], v220 offset:34816
	ds_read_b128 v[176:179], v220 offset:35840
	ds_read_b128 v[180:183], v220 offset:36864
	ds_read_b128 v[184:187], v220 offset:37888
	ds_read_b128 v[206:209], v220 offset:38912
	ds_read_b128 v[210:213], v220 offset:39936
	v_lshl_add_u64 v[238:239], s[40:41], 0, v[188:189]
	s_mov_b32 m0, s51
	s_nop 0
	s_waitcnt vmcnt(0)
	s_waitcnt lgkmcnt(0)
	v_mfma_f32_16x16x32_bf16 v[128:131], v[132:135], v[164:167], v[128:131]
	v_mfma_f32_16x16x32_bf16 v[124:127], v[140:143], v[164:167], v[124:127]
	v_mfma_f32_16x16x32_bf16 v[112:115], v[132:135], v[172:175], v[112:115]
	v_mfma_f32_16x16x32_bf16 v[108:111], v[140:143], v[172:175], v[108:111]
	s_barrier
	s_setprio 1
	v_mfma_f32_16x16x32_bf16 v[96:99], v[132:135], v[180:183], v[96:99]
	v_mfma_f32_16x16x32_bf16 v[92:95], v[140:143], v[180:183], v[92:95]
	v_mfma_f32_16x16x32_bf16 v[80:83], v[132:135], v[206:209], v[80:83]
	v_mfma_f32_16x16x32_bf16 v[76:79], v[140:143], v[206:209], v[76:79]
	v_mfma_f32_16x16x32_bf16 v[128:131], v[136:139], v[168:171], v[128:131]
	v_mfma_f32_16x16x32_bf16 v[124:127], v[144:147], v[168:171], v[124:127]
	v_mfma_f32_16x16x32_bf16 v[112:115], v[136:139], v[176:179], v[112:115]
	v_mfma_f32_16x16x32_bf16 v[108:111], v[144:147], v[176:179], v[108:111]
	v_mfma_f32_16x16x32_bf16 v[96:99], v[136:139], v[184:187], v[96:99]
	v_mfma_f32_16x16x32_bf16 v[92:95], v[144:147], v[184:187], v[92:95]
	v_mfma_f32_16x16x32_bf16 v[80:83], v[136:139], v[210:213], v[80:83]
	v_mfma_f32_16x16x32_bf16 v[76:79], v[144:147], v[210:213], v[76:79]
	s_setprio 0
	s_setprio 1
	v_mfma_f32_16x16x32_bf16 v[120:123], v[148:151], v[164:167], v[120:123]
	v_mfma_f32_16x16x32_bf16 v[116:119], v[156:159], v[164:167], v[116:119]
	v_mfma_f32_16x16x32_bf16 v[104:107], v[148:151], v[172:175], v[104:107]
	v_mfma_f32_16x16x32_bf16 v[100:103], v[156:159], v[172:175], v[100:103]
	v_mfma_f32_16x16x32_bf16 v[88:91], v[148:151], v[180:183], v[88:91]
	v_mfma_f32_16x16x32_bf16 v[84:87], v[156:159], v[180:183], v[84:87]
	v_mfma_f32_16x16x32_bf16 v[72:75], v[148:151], v[206:209], v[72:75]
	v_mfma_f32_16x16x32_bf16 v[68:71], v[156:159], v[206:209], v[68:71]
	v_mfma_f32_16x16x32_bf16 v[120:123], v[152:155], v[168:171], v[120:123]
	v_mfma_f32_16x16x32_bf16 v[116:119], v[160:163], v[168:171], v[116:119]
	v_mfma_f32_16x16x32_bf16 v[104:107], v[152:155], v[176:179], v[104:107]
	v_mfma_f32_16x16x32_bf16 v[100:103], v[160:163], v[176:179], v[100:103]
	v_mfma_f32_16x16x32_bf16 v[88:91], v[152:155], v[184:187], v[88:91]
	v_mfma_f32_16x16x32_bf16 v[84:87], v[160:163], v[184:187], v[84:87]
	v_mfma_f32_16x16x32_bf16 v[72:75], v[152:155], v[210:213], v[72:75]
	v_mfma_f32_16x16x32_bf16 v[68:71], v[160:163], v[210:213], v[68:71]
	s_setprio 0
	s_barrier
	s_add_i32 s40, s63, s47
	v_lshl_add_u64 v[214:215], v[214:215], 0, s[36:37]
	s_mov_b32 m0, s40
	ds_read_b128 v[164:167], v220 offset:49152
	ds_read_b128 v[168:171], v220 offset:50176
	ds_read_b128 v[172:175], v220 offset:51200
	ds_read_b128 v[176:179], v220 offset:52224
	ds_read_b128 v[180:183], v220 offset:53248
	ds_read_b128 v[184:187], v220 offset:54272
	ds_read_b128 v[206:209], v220 offset:55296
	ds_read_b128 v[210:213], v220 offset:56320
	v_lshl_add_u64 v[214:215], v[216:217], 0, s[36:37]
	s_add_i32 m0, s40, 0x2000
	s_add_i32 s40, s64, s47
	v_lshl_add_u64 v[214:215], v[222:223], 0, s[36:37]
	s_mov_b32 m0, s40
	s_nop 0
	v_lshl_add_u64 v[214:215], v[224:225], 0, s[36:37]
	s_add_i32 m0, s40, 0x2000
	s_nop 0
	v_lshl_add_u64 v[214:215], v[226:227], 0, s[36:37]
	s_mov_b32 m0, s52
	s_nop 0
	v_lshl_add_u64 v[214:215], v[236:237], 0, s[36:37]
	s_mov_b32 m0, s53
	s_nop 0
	s_waitcnt vmcnt(0)
	s_waitcnt lgkmcnt(0)
	v_mfma_f32_16x16x32_bf16 v[64:67], v[132:135], v[164:167], v[64:67]
	v_mfma_f32_16x16x32_bf16 v[60:63], v[140:143], v[164:167], v[60:63]
	v_mfma_f32_16x16x32_bf16 v[48:51], v[132:135], v[172:175], v[48:51]
	v_mfma_f32_16x16x32_bf16 v[44:47], v[140:143], v[172:175], v[44:47]
	s_barrier
	s_setprio 1
	v_mfma_f32_16x16x32_bf16 v[28:31], v[132:135], v[180:183], v[28:31]
	v_mfma_f32_16x16x32_bf16 v[24:27], v[140:143], v[180:183], v[24:27]
	v_mfma_f32_16x16x32_bf16 v[12:15], v[132:135], v[206:209], v[12:15]
	v_mfma_f32_16x16x32_bf16 v[8:11], v[140:143], v[206:209], v[8:11]
	v_mfma_f32_16x16x32_bf16 v[64:67], v[136:139], v[168:171], v[64:67]
	v_mfma_f32_16x16x32_bf16 v[60:63], v[144:147], v[168:171], v[60:63]
	v_mfma_f32_16x16x32_bf16 v[48:51], v[136:139], v[176:179], v[48:51]
	v_mfma_f32_16x16x32_bf16 v[44:47], v[144:147], v[176:179], v[44:47]
	v_mfma_f32_16x16x32_bf16 v[28:31], v[136:139], v[184:187], v[28:31]
	v_mfma_f32_16x16x32_bf16 v[24:27], v[144:147], v[184:187], v[24:27]
	v_mfma_f32_16x16x32_bf16 v[12:15], v[136:139], v[210:213], v[12:15]
	v_mfma_f32_16x16x32_bf16 v[8:11], v[144:147], v[210:213], v[8:11]
	s_setprio 0
	s_setprio 1
	v_mfma_f32_16x16x32_bf16 v[56:59], v[148:151], v[164:167], v[56:59]
	v_mfma_f32_16x16x32_bf16 v[52:55], v[156:159], v[164:167], v[52:55]
	v_mfma_f32_16x16x32_bf16 v[40:43], v[148:151], v[172:175], v[40:43]
	v_mfma_f32_16x16x32_bf16 v[36:39], v[156:159], v[172:175], v[36:39]
	v_mfma_f32_16x16x32_bf16 v[20:23], v[148:151], v[180:183], v[20:23]
	v_mfma_f32_16x16x32_bf16 v[16:19], v[156:159], v[180:183], v[16:19]
	v_mfma_f32_16x16x32_bf16 v[4:7], v[148:151], v[206:209], v[4:7]
	v_mfma_f32_16x16x32_bf16 v[0:3], v[156:159], v[206:209], v[0:3]
	v_mfma_f32_16x16x32_bf16 v[56:59], v[152:155], v[168:171], v[56:59]
	v_mfma_f32_16x16x32_bf16 v[52:55], v[160:163], v[168:171], v[52:55]
	v_mfma_f32_16x16x32_bf16 v[40:43], v[152:155], v[176:179], v[40:43]
	v_mfma_f32_16x16x32_bf16 v[36:39], v[160:163], v[176:179], v[36:39]
	v_mfma_f32_16x16x32_bf16 v[20:23], v[152:155], v[184:187], v[20:23]
	v_mfma_f32_16x16x32_bf16 v[16:19], v[160:163], v[184:187], v[16:19]
	v_mfma_f32_16x16x32_bf16 v[4:7], v[152:155], v[210:213], v[4:7]
	v_mfma_f32_16x16x32_bf16 v[0:3], v[160:163], v[210:213], v[0:3]
	s_setprio 0
	s_barrier
	s_add_u32 s22, s22, 0x100
	s_addc_u32 s23, s23, 0
	s_add_u32 s60, s60, 0x100
	s_addc_u32 s61, s61, 0
	s_mov_b32 s40, s62
; __device__ __forceinline__ unsigned pk2(float lo, float hi) { return pg8::cvt_pk_bf16(lo, hi); }
;     __device__ __forceinline__ void operator()(const pg8::f32x4 (&acc)[2][2][4][2], const pg8::Unit& u, int wr, int wc, int fr, int fq) const {
;         const int row0 = u.pm * 256 + wr * 64 + fr, col0 = u.pn * 256 + wc * 32 + 8 * fq;
; #pragma unroll
;         for (int ai = 0; ai < 2; ++ai) {
;             f32x4 bv[4][2][2];
; #pragma unroll
;             for (int m = 0; m < 4; ++m)
; #pragma unroll
;                 for (int bj = 0; bj < 2; ++bj) { const size_t off = (size_t)(row0 + ai * 128 + m * 16) * DM + col0 + bj * 128; bv[m][bj][0] = *(const f32x4*)(base + off); bv[m][bj][1] = *(const f32x4*)(base + off + 4); }
; #pragma unroll
;             for (int m = 0; m < 4; ++m) {
;                 const int row = row0 + ai * 128 + m * 16; float ss = 0.f;
; #pragma unroll
;                 for (int bj = 0; bj < 2; ++bj) {
;                     const size_t off = (size_t)row * DM + col0 + bj * 128;
;                     const f32x4 x0 = bv[m][bj][0] + acc[ai][bj][m][0] * alpha, x1 = bv[m][bj][1] + acc[ai][bj][m][1] * alpha;
;                     *(f32x4*)(out + off) = x0; *(f32x4*)(out + off + 4) = x1;
;                     u32x4 w; w.x = pk2(x0[0], x0[1]); w.y = pk2(x0[2], x0[3]); w.z = pk2(x1[0], x1[1]); w.w = pk2(x1[2], x1[3]);
;                     *(u32x4*)(xb + off) = w;
;                     ss += ((x0[0] * x0[0] + x0[1] * x0[1]) + (x0[2] * x0[2] + x0[3] * x0[3])) + ((x1[0] * x1[0] + x1[1] * x1[1]) + (x1[2] * x1[2] + x1[3] * x1[3]));
.Lkexit_rs:
	s_and_b64 vcc, exec, s[16:17]
	s_cbranch_vccz .LBB0_592
	s_barrier
.LBB0_592:
	v_xor_b32_e32 v132, 16, v233
	v_cmp_lt_i32_e32 vcc, v132, v234
	v_lshl_add_u32 v208, s59, 8, v35
	v_lshl_or_b32 v206, s8, 8, v219
	v_cndmask_b32_e32 v132, v233, v132, vcc
	v_lshlrev_b32_e32 v222, 2, v132
	v_xor_b32_e32 v132, 32, v233
	v_cmp_lt_i32_e32 vcc, v132, v234
	v_ashrrev_i32_e32 v207, 31, v206
	v_ashrrev_i32_e32 v209, 31, v208
	v_cndmask_b32_e32 v132, v233, v132, vcc
	v_lshlrev_b32_e32 v221, 2, v132
	v_lshl_add_u64 v[210:211], v[206:207], 2, s[12:13]
	v_lshlrev_b64 v[132:133], 12, v[208:209]
	v_lshl_add_u64 v[132:133], v[210:211], 0, v[132:133]
	global_load_dwordx4 v[224:227], v[132:133], off offset:16
	global_load_dwordx4 v[248:251], v[132:133], off
	global_load_dwordx4 v[180:183], v[132:133], off offset:528
	global_load_dwordx4 v[184:187], v[132:133], off offset:512
	v_or_b32_e32 v216, 16, v208
	v_ashrrev_i32_e32 v217, 31, v216
	v_lshlrev_b64 v[132:133], 12, v[216:217]
	v_or_b32_e32 v214, 32, v208
	v_lshl_add_u64 v[132:133], v[210:211], 0, v[132:133]
	v_ashrrev_i32_e32 v215, 31, v214
	global_load_dwordx4 v[172:175], v[132:133], off offset:16
	global_load_dwordx4 v[176:179], v[132:133], off
	global_load_dwordx4 v[164:167], v[132:133], off offset:528
	global_load_dwordx4 v[168:171], v[132:133], off offset:512
	v_lshlrev_b64 v[132:133], 12, v[214:215]
	v_or_b32_e32 v212, 48, v208
	v_lshl_add_u64 v[132:133], v[210:211], 0, v[132:133]
	v_ashrrev_i32_e32 v213, 31, v212
	global_load_dwordx4 v[156:159], v[132:133], off offset:16
	global_load_dwordx4 v[160:163], v[132:133], off
	global_load_dwordx4 v[140:143], v[132:133], off offset:528
	global_load_dwordx4 v[148:151], v[132:133], off offset:512
	v_lshlrev_b64 v[132:133], 12, v[212:213]
	v_lshl_add_u64 v[136:137], v[210:211], 0, v[132:133]
	global_load_dwordx4 v[144:147], v[136:137], off offset:16
	global_load_dwordx4 v[152:155], v[136:137], off
	global_load_dwordx4 v[132:135], v[136:137], off offset:528
	s_nop 0
	global_load_dwordx4 v[136:139], v[136:137], off offset:512
	v_lshlrev_b64 v[236:237], 10, v[208:209]
	v_lshl_add_u64 v[236:237], v[236:237], 0, v[206:207]
	v_mov_b32_e32 v193, v192
	v_lshl_add_u64 v[238:239], v[236:237], 2, s[24:25]
	v_lshlrev_b64 v[236:237], 1, v[236:237]
	v_lshl_add_u64 v[240:241], s[2:3], 0, v[236:237]
	s_lshl_b32 s22, s8, 2
	v_or_b32_e32 v236, 0x100, v236
	s_ashr_i32 s23, s22, 31
	s_waitcnt vmcnt(0)
	v_pk_fma_f32 v[124:125], v[194:195], v[124:125], v[224:225]
	v_pk_fma_f32 v[130:131], v[192:193], v[130:131], v[250:251]
	v_pk_fma_f32 v[128:129], v[194:195], v[128:129], v[248:249]
	v_pk_fma_f32 v[126:127], v[192:193], v[126:127], v[226:227]
	global_store_dwordx4 v[238:239], v[128:131], off
	global_store_dwordx4 v[238:239], v[124:127], off offset:16
	v_cvt_pk_bf16_f32 v224, v128, v129
	v_cvt_pk_bf16_f32 v226, v124, v125
	v_mul_f32_e32 v129, v129, v129
	v_mul_f32_e32 v125, v125, v125
	v_fmac_f32_e32 v129, v128, v128
	v_mul_f32_e32 v128, v131, v131
	v_fmac_f32_e32 v125, v124, v124
	v_mul_f32_e32 v124, v127, v127
	v_fmac_f32_e32 v128, v130, v130
	v_fmac_f32_e32 v124, v126, v126
	v_cvt_pk_bf16_f32 v225, v130, v131
	v_cvt_pk_bf16_f32 v227, v126, v127
	v_add_f32_e32 v128, v129, v128
	v_add_f32_e32 v124, v125, v124
	v_pk_fma_f32 v[122:123], v[192:193], v[122:123], v[186:187]
	v_pk_fma_f32 v[120:121], v[194:195], v[120:121], v[184:185]
	v_pk_fma_f32 v[116:117], v[194:195], v[116:117], v[180:181]
	s_cmp_eq_u32 s28, 32
	s_cbranch_scc1 .Lxbskip_15
	global_store_dwordx4 v[240:241], v[224:227], off
